# second-to-last arriver of each XCD starts an un-waited L2 write-back so that the last arriver's release flush is short
# baseline (speedup 1.0000x reference)
.Lmy_xb4_have:
	v_mov_b32_e32 v0, s9
	v_mov_b32_e32 v4, 1
	global_atomic_add v4, v0, v4, s[36:37] sc0
	v_cvt_f32_u32_e32 v5, v3
	v_rcp_f32_e32 v5, v5
	s_waitcnt vmcnt(0)
	v_cvt_f32_u32_e32 v0, v4
	v_add_f32_e32 v0, 0.5, v0
	v_mul_f32_e32 v0, v0, v5
	v_cvt_u32_f32_e32 v0, v0
	v_add_u32_e32 v0, 1, v0
	v_mul_lo_u32 v5, v0, v3
	v_mul_lo_u32 v2, v0, v2
	v_add_u32_e32 v4, 1, v4
	v_mov_b32_e32 v0, s10
	v_add_u32_e32 v3, 1, v4
	v_cmp_ne_u32_e32 vcc, v3, v5
	s_cbranch_vccnz .Lmy_pf0
	buffer_wbl2 sc1
.Lmy_pf0:
	v_cmp_ne_u32_e32 vcc, v4, v5
	s_cbranch_vccnz .Lmy_xb4_poll
	buffer_wbl2 sc1
	s_waitcnt vmcnt(0)
	v_mov_b32_e32 v4, 1
	v_mov_b32_e32 v3, 0x4000
	global_atomic_add v3, v4, s[36:37]
	v_mov_b32_e32 v3, 0x4100
	global_atomic_add v3, v4, s[36:37]
	v_mov_b32_e32 v3, 0x4200
	global_atomic_add v3, v4, s[36:37]
	v_mov_b32_e32 v3, 0x4300
	global_atomic_add v3, v4, s[36:37]
	v_mov_b32_e32 v3, 0x4400
	global_atomic_add v3, v4, s[36:37]
	v_mov_b32_e32 v3, 0x4500
	global_atomic_add v3, v4, s[36:37]
	v_mov_b32_e32 v3, 0x4600
	global_atomic_add v3, v4, s[36:37]
	v_mov_b32_e32 v3, 0x4700
	global_atomic_add v3, v4, s[36:37]
	v_mov_b32_e32 v3, 0x4800
	global_atomic_add v3, v4, s[36:37]
	v_mov_b32_e32 v3, 0x4900
	global_atomic_add v3, v4, s[36:37]
	v_mov_b32_e32 v3, 0x4a00
	global_atomic_add v3, v4, s[36:37]
	v_mov_b32_e32 v3, 0x4b00
	global_atomic_add v3, v4, s[36:37]
	v_mov_b32_e32 v3, 0x4c00
	global_atomic_add v3, v4, s[36:37]
	v_mov_b32_e32 v3, 0x4d00
	global_atomic_add v3, v4, s[36:37]
	v_mov_b32_e32 v3, 0x4e00
	global_atomic_add v3, v4, s[36:37]
	v_mov_b32_e32 v3, 0x4f00
	global_atomic_add v3, v4, s[36:37]

.LBB0_489:
	s_getreg_b32 s6, hwreg(HW_REG_XCC_ID, 0, 4)
	s_waitcnt vmcnt(0)
	s_barrier
	s_and_saveexec_b64 s[4:5], s[74:75]
	s_cbranch_execz .Lmy_sb_mid
	v_readlane_b32 s7, v255, 10
	v_readlane_b32 s8, v255, 11
	s_and_b32 s6, s6, 15
	s_lshl_b32 s6, s6, 8
	v_mov_b32_e32 v0, s7
	v_mov_b32_e32 v2, s8
	ds_read_b32 v3, v0
	ds_read_b32 v2, v2
	s_add_i32 s9, s6, 0x1400
	s_add_i32 s10, s6, 0x4000
	s_waitcnt vmcnt(0) lgkmcnt(0)
	v_mov_b32_e32 v0, s9
	v_mov_b32_e32 v4, 1
	global_atomic_add v4, v0, v4, s[36:37] sc0
	v_cvt_f32_u32_e32 v5, v3
	v_rcp_f32_e32 v5, v5
	s_waitcnt vmcnt(0)
	v_cvt_f32_u32_e32 v0, v4
	v_add_f32_e32 v0, 0.5, v0
	v_mul_f32_e32 v0, v0, v5
	v_cvt_u32_f32_e32 v0, v0
	v_add_u32_e32 v0, 1, v0
	v_mul_lo_u32 v5, v0, v3
	v_mul_lo_u32 v2, v0, v2
	v_add_u32_e32 v4, 1, v4
	v_mov_b32_e32 v0, s10
	v_add_u32_e32 v3, 1, v4
	v_cmp_ne_u32_e32 vcc, v3, v5
	s_cbranch_vccnz .Lmy_pf1
	buffer_wbl2 sc1

.LBB0_974:
	s_getreg_b32 s6, hwreg(HW_REG_XCC_ID, 0, 4)
	s_waitcnt vmcnt(0)
	s_waitcnt lgkmcnt(0)
	s_barrier
	s_and_saveexec_b64 s[4:5], s[74:75]
	s_cbranch_execz .LBB0_1026
	v_readlane_b32 s7, v255, 10
	v_readlane_b32 s8, v255, 11
	s_and_b32 s6, s6, 15
	s_lshl_b32 s6, s6, 8
	v_mov_b32_e32 v0, s7
	v_mov_b32_e32 v2, s8
	ds_read_b32 v3, v0
	ds_read_b32 v2, v2
	s_add_i32 s9, s6, 0x1400
	s_add_i32 s10, s6, 0x4000
	s_waitcnt vmcnt(0) lgkmcnt(0)
	v_mov_b32_e32 v0, s9
	v_mov_b32_e32 v4, 1
	global_atomic_add v4, v0, v4, s[36:37] sc0
	v_cvt_f32_u32_e32 v5, v3
	v_rcp_f32_e32 v5, v5
	s_waitcnt vmcnt(0)
	v_cvt_f32_u32_e32 v0, v4
	v_add_f32_e32 v0, 0.5, v0
	v_mul_f32_e32 v0, v0, v5
	v_cvt_u32_f32_e32 v0, v0
	v_add_u32_e32 v0, 1, v0
	v_mul_lo_u32 v5, v0, v3
	v_mul_lo_u32 v2, v0, v2
	v_add_u32_e32 v4, 1, v4
	v_mov_b32_e32 v0, s10
	v_add_u32_e32 v3, 1, v4
	v_cmp_ne_u32_e32 vcc, v3, v5
	s_cbranch_vccnz .Lmy_pf3
	buffer_wbl2 sc1

.LBB0_1186:
	s_cmp_eq_u32 s40, 7
	v_readlane_b32 s26, v255, 37
	v_readlane_b32 s27, v255, 38
	s_cbranch_scc1 .LBB0_161
	s_getreg_b32 s6, hwreg(HW_REG_XCC_ID, 0, 4)
	s_waitcnt vmcnt(0)
	s_barrier
	s_and_saveexec_b64 s[4:5], s[74:75]
	s_cbranch_execz .LBB0_160
	v_readlane_b32 s7, v255, 10
	v_readlane_b32 s8, v255, 11
	s_and_b32 s6, s6, 15
	s_lshl_b32 s6, s6, 8
	v_mov_b32_e32 v0, s7
	v_mov_b32_e32 v2, s8
	ds_read_b32 v3, v0
	ds_read_b32 v2, v2
	s_add_i32 s9, s6, 0x1400
	s_add_i32 s10, s6, 0x4000
	s_waitcnt vmcnt(0) lgkmcnt(0)
	v_mov_b32_e32 v0, s9
	v_mov_b32_e32 v4, 1
	global_atomic_add v4, v0, v4, s[36:37] sc0
	v_cvt_f32_u32_e32 v5, v3
	v_rcp_f32_e32 v5, v5
	s_waitcnt vmcnt(0)
	v_cvt_f32_u32_e32 v0, v4
	v_add_f32_e32 v0, 0.5, v0
	v_mul_f32_e32 v0, v0, v5
	v_cvt_u32_f32_e32 v0, v0
	v_add_u32_e32 v0, 1, v0
	v_mul_lo_u32 v5, v0, v3
	v_mul_lo_u32 v2, v0, v2
	v_add_u32_e32 v4, 1, v4
	v_mov_b32_e32 v0, s10
	v_add_u32_e32 v3, 1, v4
	v_cmp_ne_u32_e32 vcc, v3, v5
	s_cbranch_vccnz .Lmy_pf4
	buffer_wbl2 sc1
